# local attention half: V^T fragment addresses of chunks 2..7 folded into ds_read offset immediates (18 fewer VALU per item)
# speedup vs baseline: 1.0022x; 1.0022x over previous
; __device__ __forceinline__ unsigned cvt_pk_bf16(float lo, float hi) { const f32x2 v = (f32x2){lo, hi}; return __builtin_bit_cast(unsigned, __builtin_convertvector(v, bf16v2)); }
; #define AH_LDV(c, bufi) do { const int vaddr = vrow + (((vchunk0 + (c) * vcs + g) ^ qi) << 4); _Pragma("unroll") for (int dt = 0; dt < 4; ++dt) vf[bufi][dt] = *(const LAS bf16x8*)(lds + vaddr + dt * vpitch_dt); } while (0)
; template <bool LOC> ...
;     ...
;     float m2 = mx;
; #pragma unroll
;     for (int c = 0; c < 8; ++c)
; #pragma unroll
;         for (int e = 0; e < 8; ++e) m2 = fmaxf(m2, s[c][e]);
;     m2 = fmaxf(m2, __shfl_xor(m2, 16)); m2 = fmaxf(m2, __shfl_xor(m2, 32));
;     const float alpha = __builtin_amdgcn_exp2f(mx - m2);
;     mx = m2; lsum *= alpha;
; #pragma unroll
;     for (int dt = 0; dt < 4; ++dt) o[dt] = o[dt] * alpha;
;     bf16x8 vf[2][4];
;     ...
;     AH_LDV(0, 0);
; #pragma unroll
;     for (int c = 0; c < 8; ++c) {
;         if (c < 7) AH_LDV(c + 1, (c + 1) & 1);
;         __builtin_amdgcn_sched_barrier(0);
;         float pe[8];
; #pragma unroll
;         for (int e = 0; e < 8; ++e) { pe[e] = __builtin_amdgcn_exp2f(s[c][e] - mx); lsum += pe[e]; }
;         u32x4 pw; pw.x = cvt_pk_bf16(pe[0], pe[1]); pw.y = cvt_pk_bf16(pe[2], pe[3]); pw.z = cvt_pk_bf16(pe[4], pe[5]); pw.w = cvt_pk_bf16(pe[6], pe[7]);
;         const bf16x8 pb = __builtin_bit_cast(bf16x8, pw);
; #pragma unroll
;         for (int dt = 0; dt < 4; ++dt) o[dt] = __builtin_amdgcn_mfma_f32_16x16x32_bf16(vf[c & 1][dt], pb, o[dt], 0, 0, 0);
;         __builtin_amdgcn_sched_barrier(0);
;     }
.Lm_noctx:
	v_max3_f32 v0, v97, v30, v29
	v_max3_f32 v0, v0, v32, v31
	v_max3_f32 v0, v0, v34, v33
	v_max3_f32 v0, v0, v43, v41
	v_max3_f32 v0, v0, v37, v35
	v_max3_f32 v0, v0, v39, v38
	v_max3_f32 v0, v0, v42, v40
	v_max3_f32 v0, v0, v51, v49
	v_max3_f32 v0, v0, v45, v44
	v_max3_f32 v0, v0, v47, v46
	v_max3_f32 v0, v0, v50, v48
	v_max3_f32 v0, v0, v59, v57
	v_max3_f32 v0, v0, v53, v52
	v_max3_f32 v0, v0, v55, v54
	v_max3_f32 v0, v0, v58, v56
	v_max3_f32 v0, v0, v67, v65
	v_max3_f32 v0, v0, v61, v60
	v_max3_f32 v0, v0, v63, v62
	v_max3_f32 v0, v0, v66, v64
	v_max3_f32 v0, v0, v102, v100
	v_max3_f32 v0, v0, v69, v68
	v_max3_f32 v0, v0, v71, v70
	v_max3_f32 v0, v0, v101, v99
	v_max3_f32 v0, v0, v155, v153
	v_max3_f32 v0, v0, v104, v103
	v_max3_f32 v0, v0, v151, v105
	v_max3_f32 v0, v0, v154, v152
	v_max3_f32 v0, v0, v175, v173
	v_max3_f32 v0, v0, v170, v167
	v_max3_f32 v0, v0, v172, v171
	v_max3_f32 v0, v0, v176, v174
	v_max3_f32 v0, v0, v178, v177
	ds_bpermute_b32 v1, v114, v0
	s_waitcnt lgkmcnt(0)
	v_max_f32_e32 v1, v1, v1
	v_max_f32_e32 v0, v0, v1
	ds_bpermute_b32 v1, v115, v0
	s_waitcnt lgkmcnt(0)
	v_max_f32_e32 v1, v1, v1
	v_max_f32_e32 v179, v0, v1
	v_sub_f32_e32 v0, v97, v179
	v_exp_f32_e32 v204, v0
	s_nop 0
	v_pk_mul_f32 v[24:25], v[8:9], v[204:205] op_sel_hi:[1,0]
	v_pk_mul_f32 v[8:9], v[12:13], v[204:205] op_sel_hi:[1,0]
	v_lshl_add_u32 v12, v36, 3, v112
	v_xor_b32_e32 v234, v12, v107
	v_lshl_add_u32 v234, v234, 4, v113
	v_pk_mul_f32 v[26:27], v[10:11], v[204:205] op_sel_hi:[1,0]
	v_pk_mul_f32 v[10:11], v[14:15], v[204:205] op_sel_hi:[1,0]
	v_pk_mul_f32 v[6:7], v[18:19], v[204:205] op_sel_hi:[1,0]
	v_pk_mul_f32 v[4:5], v[16:17], v[204:205] op_sel_hi:[1,0]
	v_pk_mul_f32 v[0:1], v[20:21], v[204:205] op_sel_hi:[1,0]
	ds_read_b128 v[14:17], v234
	ds_read_b128 v[18:21], v234 offset:20480
	ds_read_b128 v[180:183], v234 offset:40960
	ds_read_b128 v[184:187], v234 offset:61440
	v_add_u32_e32 v249, 8, v12
	v_xor_b32_e32 v249, v249, v107
	v_lshl_add_u32 v249, v249, 4, v113
	ds_read_b128 v[188:191], v249
	ds_read_b128 v[192:195], v249 offset:20480
	ds_read_b128 v[196:199], v249 offset:40960
	ds_read_b128 v[200:203], v249 offset:61440
	v_pk_mul_f32 v[2:3], v[22:23], v[204:205] op_sel_hi:[1,0]
	v_mul_f32_e32 v218, v28, v204
	v_mov_b32_e32 v219, 0
	v_sub_f32_e32 v224, v30, v179
	v_sub_f32_e32 v225, v29, v179
	v_exp_f32_e32 v224, v224
	v_sub_f32_e32 v226, v32, v179
	v_exp_f32_e32 v225, v225
	v_sub_f32_e32 v227, v31, v179
	v_exp_f32_e32 v226, v226
	v_sub_f32_e32 v228, v34, v179
	v_exp_f32_e32 v227, v227
	v_sub_f32_e32 v229, v33, v179
	v_exp_f32_e32 v228, v228
	v_pk_add_f32 v[218:219], v[218:219], v[224:225]
	v_sub_f32_e32 v230, v43, v179
	v_exp_f32_e32 v229, v229
	v_pk_add_f32 v[218:219], v[218:219], v[226:227]
	v_sub_f32_e32 v231, v41, v179
	v_exp_f32_e32 v230, v230
	v_cvt_pk_bf16_f32 v28, v224, v225
	v_exp_f32_e32 v231, v231
	v_cvt_pk_bf16_f32 v29, v226, v227
	v_pk_add_f32 v[218:219], v[218:219], v[228:229]
	v_cvt_pk_bf16_f32 v30, v228, v229
	v_cvt_pk_bf16_f32 v31, v230, v231
	v_pk_add_f32 v[218:219], v[218:219], v[230:231]
	s_waitcnt lgkmcnt(4)
	v_mfma_f32_16x16x32_bf16 v[14:17], v[14:17], v[28:31], v[24:27]
	v_mfma_f32_16x16x32_bf16 v[8:11], v[18:21], v[28:31], v[8:11]
	v_mfma_f32_16x16x32_bf16 v[4:7], v[180:183], v[28:31], v[4:7]
	v_mfma_f32_16x16x32_bf16 v[0:3], v[184:187], v[28:31], v[0:3]
	ds_read_b128 v[18:21], v234 offset:256
	ds_read_b128 v[22:25], v234 offset:20736
	ds_read_b128 v[26:29], v234 offset:41216
	ds_read_b128 v[30:33], v234 offset:61696
	v_sub_f32_e32 v224, v37, v179
	v_sub_f32_e32 v225, v35, v179
	v_exp_f32_e32 v224, v224
	v_sub_f32_e32 v226, v39, v179
	v_exp_f32_e32 v225, v225
	v_sub_f32_e32 v227, v38, v179
	v_exp_f32_e32 v226, v226
	v_sub_f32_e32 v228, v42, v179
	v_exp_f32_e32 v227, v227
	v_sub_f32_e32 v229, v40, v179
	v_exp_f32_e32 v228, v228
	v_pk_add_f32 v[218:219], v[218:219], v[224:225]
	v_sub_f32_e32 v230, v51, v179
	v_exp_f32_e32 v229, v229
	v_pk_add_f32 v[218:219], v[218:219], v[226:227]
	v_sub_f32_e32 v231, v49, v179
	v_exp_f32_e32 v230, v230
	v_cvt_pk_bf16_f32 v34, v224, v225
	v_exp_f32_e32 v231, v231
	v_cvt_pk_bf16_f32 v35, v226, v227
	v_pk_add_f32 v[218:219], v[218:219], v[228:229]
	v_cvt_pk_bf16_f32 v36, v228, v229
	v_cvt_pk_bf16_f32 v37, v230, v231
	v_pk_add_f32 v[218:219], v[218:219], v[230:231]
	s_waitcnt lgkmcnt(4)
	s_nop 0
	v_mfma_f32_16x16x32_bf16 v[14:17], v[188:191], v[34:37], v[14:17]
	v_mfma_f32_16x16x32_bf16 v[8:11], v[192:195], v[34:37], v[8:11]
	v_mfma_f32_16x16x32_bf16 v[4:7], v[196:199], v[34:37], v[4:7]
	v_mfma_f32_16x16x32_bf16 v[0:3], v[200:203], v[34:37], v[0:3]
	ds_read_b128 v[34:37], v249 offset:256
	ds_read_b128 v[38:41], v249 offset:20736
	ds_read_b128 v[180:183], v249 offset:41216
	ds_read_b128 v[184:187], v249 offset:61696
	v_sub_f32_e32 v224, v45, v179
	v_sub_f32_e32 v225, v44, v179
	v_exp_f32_e32 v224, v224
	v_sub_f32_e32 v226, v47, v179
	v_exp_f32_e32 v225, v225
	v_sub_f32_e32 v227, v46, v179
	v_exp_f32_e32 v226, v226
	v_sub_f32_e32 v228, v50, v179
	v_exp_f32_e32 v227, v227
	v_sub_f32_e32 v229, v48, v179
	v_exp_f32_e32 v228, v228
	v_pk_add_f32 v[218:219], v[218:219], v[224:225]
	v_sub_f32_e32 v230, v59, v179
	v_exp_f32_e32 v229, v229
	v_pk_add_f32 v[218:219], v[218:219], v[226:227]
	v_sub_f32_e32 v231, v57, v179
	v_exp_f32_e32 v230, v230
	v_cvt_pk_bf16_f32 v42, v224, v225
	v_exp_f32_e32 v231, v231
	v_cvt_pk_bf16_f32 v43, v226, v227
	v_pk_add_f32 v[218:219], v[218:219], v[228:229]
	v_cvt_pk_bf16_f32 v44, v228, v229
	v_cvt_pk_bf16_f32 v45, v230, v231
	v_pk_add_f32 v[218:219], v[218:219], v[230:231]
	s_waitcnt lgkmcnt(4)
; __device__ __forceinline__ unsigned cvt_pk_bf16(float lo, float hi) { const f32x2 v = (f32x2){lo, hi}; return __builtin_bit_cast(unsigned, __builtin_convertvector(v, bf16v2)); }
; #define AH_LDV(c, bufi) do { const int vaddr = vrow + (((vchunk0 + (c) * vcs + g) ^ qi) << 4); _Pragma("unroll") for (int dt = 0; dt < 4; ++dt) vf[bufi][dt] = *(const LAS bf16x8*)(lds + vaddr + dt * vpitch_dt); } while (0)
; template <bool LOC> ...
;     ...
;     AH_LDV(0, 0);
; #pragma unroll
;     for (int c = 0; c < 8; ++c) {
;         if (c < 7) AH_LDV(c + 1, (c + 1) & 1);
;         __builtin_amdgcn_sched_barrier(0);
;         float pe[8];
; #pragma unroll
;         for (int e = 0; e < 8; ++e) { pe[e] = __builtin_amdgcn_exp2f(s[c][e] - mx); lsum += pe[e]; }
;         u32x4 pw; pw.x = cvt_pk_bf16(pe[0], pe[1]); pw.y = cvt_pk_bf16(pe[2], pe[3]); pw.z = cvt_pk_bf16(pe[4], pe[5]); pw.w = cvt_pk_bf16(pe[6], pe[7]);
;         const bf16x8 pb = __builtin_bit_cast(bf16x8, pw);
; #pragma unroll
;         for (int dt = 0; dt < 4; ++dt) o[dt] = __builtin_amdgcn_mfma_f32_16x16x32_bf16(vf[c & 1][dt], pb, o[dt], 0, 0, 0);
;         __builtin_amdgcn_sched_barrier(0);
;     }
	s_nop 0
	v_mfma_f32_16x16x32_bf16 v[14:17], v[18:21], v[42:45], v[14:17]
	v_mfma_f32_16x16x32_bf16 v[8:11], v[22:25], v[42:45], v[8:11]
	v_mfma_f32_16x16x32_bf16 v[4:7], v[26:29], v[42:45], v[4:7]
	v_mfma_f32_16x16x32_bf16 v[0:3], v[30:33], v[42:45], v[0:3]
	ds_read_b128 v[18:21], v234 offset:512
	ds_read_b128 v[22:25], v234 offset:20992
	ds_read_b128 v[26:29], v234 offset:41472
	ds_read_b128 v[30:33], v234 offset:61952
	v_sub_f32_e32 v224, v53, v179
	v_sub_f32_e32 v225, v52, v179
	v_exp_f32_e32 v224, v224
	v_sub_f32_e32 v226, v55, v179
	v_exp_f32_e32 v225, v225
	v_sub_f32_e32 v227, v54, v179
	v_exp_f32_e32 v226, v226
	v_sub_f32_e32 v228, v58, v179
	v_exp_f32_e32 v227, v227
	v_sub_f32_e32 v229, v56, v179
	v_exp_f32_e32 v228, v228
	v_pk_add_f32 v[218:219], v[218:219], v[224:225]
	v_sub_f32_e32 v230, v67, v179
	v_exp_f32_e32 v229, v229
	v_pk_add_f32 v[218:219], v[218:219], v[226:227]
	v_sub_f32_e32 v231, v65, v179
	v_exp_f32_e32 v230, v230
	v_cvt_pk_bf16_f32 v42, v224, v225
	v_exp_f32_e32 v231, v231
	v_cvt_pk_bf16_f32 v43, v226, v227
	v_pk_add_f32 v[218:219], v[218:219], v[228:229]
	v_cvt_pk_bf16_f32 v44, v228, v229
	v_cvt_pk_bf16_f32 v45, v230, v231
	v_pk_add_f32 v[218:219], v[218:219], v[230:231]
	s_waitcnt lgkmcnt(4)
	s_nop 0
	v_mfma_f32_16x16x32_bf16 v[14:17], v[34:37], v[42:45], v[14:17]
	v_mfma_f32_16x16x32_bf16 v[8:11], v[38:41], v[42:45], v[8:11]
	v_mfma_f32_16x16x32_bf16 v[4:7], v[180:183], v[42:45], v[4:7]
	v_mfma_f32_16x16x32_bf16 v[0:3], v[184:187], v[42:45], v[0:3]
	ds_read_b128 v[34:37], v249 offset:512
	ds_read_b128 v[38:41], v249 offset:20992
	ds_read_b128 v[42:45], v249 offset:41472
	ds_read_b128 v[46:49], v249 offset:61952
	v_sub_f32_e32 v224, v61, v179
	v_sub_f32_e32 v225, v60, v179
	v_exp_f32_e32 v224, v224
	v_sub_f32_e32 v226, v63, v179
	v_exp_f32_e32 v225, v225
	v_sub_f32_e32 v227, v62, v179
	v_exp_f32_e32 v226, v226
	v_sub_f32_e32 v228, v66, v179
	v_exp_f32_e32 v227, v227
	v_sub_f32_e32 v229, v64, v179
	v_exp_f32_e32 v228, v228
	v_pk_add_f32 v[218:219], v[218:219], v[224:225]
	v_sub_f32_e32 v230, v102, v179
	v_exp_f32_e32 v229, v229
	v_pk_add_f32 v[218:219], v[218:219], v[226:227]
	v_sub_f32_e32 v231, v100, v179
	v_exp_f32_e32 v230, v230
	v_cvt_pk_bf16_f32 v50, v224, v225
	v_exp_f32_e32 v231, v231
	v_cvt_pk_bf16_f32 v51, v226, v227
	v_pk_add_f32 v[218:219], v[218:219], v[228:229]
	v_cvt_pk_bf16_f32 v52, v228, v229
	v_cvt_pk_bf16_f32 v53, v230, v231
	v_pk_add_f32 v[218:219], v[218:219], v[230:231]
	s_waitcnt lgkmcnt(4)
	s_nop 0
	v_mfma_f32_16x16x32_bf16 v[14:17], v[18:21], v[50:53], v[14:17]
	v_mfma_f32_16x16x32_bf16 v[8:11], v[22:25], v[50:53], v[8:11]
	v_mfma_f32_16x16x32_bf16 v[4:7], v[26:29], v[50:53], v[4:7]
	v_mfma_f32_16x16x32_bf16 v[0:3], v[30:33], v[50:53], v[0:3]
	ds_read_b128 v[18:21], v234 offset:768
	ds_read_b128 v[22:25], v234 offset:21248
	ds_read_b128 v[26:29], v234 offset:41728
	ds_read_b128 v[30:33], v234 offset:62208
	v_sub_f32_e32 v224, v69, v179
	v_sub_f32_e32 v225, v68, v179
	v_exp_f32_e32 v224, v224
	v_sub_f32_e32 v226, v71, v179
	v_exp_f32_e32 v225, v225
	v_sub_f32_e32 v227, v70, v179
	v_exp_f32_e32 v226, v226
	v_sub_f32_e32 v228, v101, v179
	v_exp_f32_e32 v227, v227
	v_sub_f32_e32 v229, v99, v179
	v_exp_f32_e32 v228, v228
	v_pk_add_f32 v[218:219], v[218:219], v[224:225]
	v_sub_f32_e32 v230, v155, v179
	v_exp_f32_e32 v229, v229
	v_pk_add_f32 v[218:219], v[218:219], v[226:227]
	v_sub_f32_e32 v231, v153, v179
	v_exp_f32_e32 v230, v230
	v_cvt_pk_bf16_f32 v50, v224, v225
	v_exp_f32_e32 v231, v231
	v_cvt_pk_bf16_f32 v51, v226, v227
	v_pk_add_f32 v[218:219], v[218:219], v[228:229]
	v_cvt_pk_bf16_f32 v52, v228, v229
	v_cvt_pk_bf16_f32 v53, v230, v231
	v_pk_add_f32 v[218:219], v[218:219], v[230:231]
	s_waitcnt lgkmcnt(4)
; __device__ __forceinline__ unsigned cvt_pk_bf16(float lo, float hi) { const f32x2 v = (f32x2){lo, hi}; return __builtin_bit_cast(unsigned, __builtin_convertvector(v, bf16v2)); }
; #define AH_LDV(c, bufi) do { const int vaddr = vrow + (((vchunk0 + (c) * vcs + g) ^ qi) << 4); _Pragma("unroll") for (int dt = 0; dt < 4; ++dt) vf[bufi][dt] = *(const LAS bf16x8*)(lds + vaddr + dt * vpitch_dt); } while (0)
; template <bool LOC> ...
;     ...
;     AH_LDV(0, 0);
; #pragma unroll
;     for (int c = 0; c < 8; ++c) {
;         if (c < 7) AH_LDV(c + 1, (c + 1) & 1);
;         __builtin_amdgcn_sched_barrier(0);
;         float pe[8];
; #pragma unroll
;         for (int e = 0; e < 8; ++e) { pe[e] = __builtin_amdgcn_exp2f(s[c][e] - mx); lsum += pe[e]; }
;         u32x4 pw; pw.x = cvt_pk_bf16(pe[0], pe[1]); pw.y = cvt_pk_bf16(pe[2], pe[3]); pw.z = cvt_pk_bf16(pe[4], pe[5]); pw.w = cvt_pk_bf16(pe[6], pe[7]);
;         const bf16x8 pb = __builtin_bit_cast(bf16x8, pw);
; #pragma unroll
;         for (int dt = 0; dt < 4; ++dt) o[dt] = __builtin_amdgcn_mfma_f32_16x16x32_bf16(vf[c & 1][dt], pb, o[dt], 0, 0, 0);
;         __builtin_amdgcn_sched_barrier(0);
;     }
;     ...
; }
; __device__ __forceinline__ void attn_store(bf16_t* MIX, int qtok, int h, int g, float lsum, const f32x4 (&o)[4]) {
;     lsum += __shfl_xor(lsum, 16); lsum += __shfl_xor(lsum, 32);
;     const float inv = 1.f / lsum;
;     bf16_t* op = MIX + (size_t)qtok * DM + 512 + h * 64 + 4 * g;
; #pragma unroll
;     for (int dt = 0; dt < 4; ++dt) { u32x2 w; w.x = cvt_pk_bf16(o[dt][0] * inv, o[dt][1] * inv); w.y = cvt_pk_bf16(o[dt][2] * inv, o[dt][3] * inv); *(u32x2*)(op + 16 * dt) = w; }
; }
	s_nop 0
	v_mfma_f32_16x16x32_bf16 v[14:17], v[34:37], v[50:53], v[14:17]
	v_mfma_f32_16x16x32_bf16 v[8:11], v[38:41], v[50:53], v[8:11]
	v_mfma_f32_16x16x32_bf16 v[4:7], v[42:45], v[50:53], v[4:7]
	v_mfma_f32_16x16x32_bf16 v[0:3], v[46:49], v[50:53], v[0:3]
	ds_read_b128 v[34:37], v249 offset:768
	ds_read_b128 v[38:41], v249 offset:21248
	ds_read_b128 v[42:45], v249 offset:41728
	ds_read_b128 v[46:49], v249 offset:62208
	v_sub_f32_e32 v224, v104, v179
	v_sub_f32_e32 v225, v103, v179
	v_exp_f32_e32 v224, v224
	v_sub_f32_e32 v226, v151, v179
	v_exp_f32_e32 v225, v225
	v_sub_f32_e32 v227, v105, v179
	v_exp_f32_e32 v226, v226
	v_sub_f32_e32 v228, v154, v179
	v_exp_f32_e32 v227, v227
	v_sub_f32_e32 v229, v152, v179
	v_exp_f32_e32 v228, v228
	v_pk_add_f32 v[218:219], v[218:219], v[224:225]
	v_sub_f32_e32 v230, v175, v179
	v_exp_f32_e32 v229, v229
	v_pk_add_f32 v[218:219], v[218:219], v[226:227]
	v_sub_f32_e32 v231, v173, v179
	v_exp_f32_e32 v230, v230
	v_cvt_pk_bf16_f32 v50, v224, v225
	v_exp_f32_e32 v231, v231
	v_cvt_pk_bf16_f32 v51, v226, v227
	v_pk_add_f32 v[218:219], v[218:219], v[228:229]
	v_cvt_pk_bf16_f32 v52, v228, v229
	v_cvt_pk_bf16_f32 v53, v230, v231
	v_pk_add_f32 v[218:219], v[218:219], v[230:231]
	s_waitcnt lgkmcnt(4)
	v_mfma_f32_16x16x32_bf16 v[12:15], v[18:21], v[50:53], v[14:17]
	v_mfma_f32_16x16x32_bf16 v[8:11], v[22:25], v[50:53], v[8:11]
	v_mfma_f32_16x16x32_bf16 v[4:7], v[26:29], v[50:53], v[4:7]
	v_mfma_f32_16x16x32_bf16 v[0:3], v[30:33], v[50:53], v[0:3]
	v_sub_f32_e32 v224, v170, v179
	v_sub_f32_e32 v225, v167, v179
	v_exp_f32_e32 v224, v224
	v_sub_f32_e32 v226, v172, v179
	v_exp_f32_e32 v225, v225
	v_sub_f32_e32 v227, v171, v179
	v_exp_f32_e32 v226, v226
	v_sub_f32_e32 v228, v176, v179
	v_exp_f32_e32 v227, v227
	v_sub_f32_e32 v229, v174, v179
	v_exp_f32_e32 v228, v228
	v_pk_add_f32 v[218:219], v[218:219], v[224:225]
	v_sub_f32_e32 v230, v178, v179
	v_exp_f32_e32 v229, v229
	v_pk_add_f32 v[218:219], v[218:219], v[226:227]
	v_sub_f32_e32 v231, v177, v179
	v_exp_f32_e32 v230, v230
	v_cvt_pk_bf16_f32 v16, v224, v225
	v_exp_f32_e32 v231, v231
	v_cvt_pk_bf16_f32 v17, v226, v227
	v_pk_add_f32 v[218:219], v[218:219], v[228:229]
	v_cvt_pk_bf16_f32 v18, v228, v229
	v_cvt_pk_bf16_f32 v19, v230, v231
	v_pk_add_f32 v[218:219], v[218:219], v[230:231]
	v_add_f32_e32 v25, v218, v219
	s_waitcnt lgkmcnt(0)
	s_nop 0
	v_mfma_f32_16x16x32_bf16 v[12:15], v[34:37], v[16:19], v[12:15]
	v_mfma_f32_16x16x32_bf16 v[8:11], v[38:41], v[16:19], v[8:11]
	v_mfma_f32_16x16x32_bf16 v[4:7], v[42:45], v[16:19], v[4:7]
	v_mfma_f32_16x16x32_bf16 v[0:3], v[46:49], v[16:19], v[0:3]
	ds_bpermute_b32 v17, v114, v25
	v_or_b32_e32 v16, s62, v108
	v_mov_b32_e32 v99, v157
	s_add_i32 s61, s61, s3
	s_cmpk_gt_i32 s61, 0x7ff
	s_waitcnt lgkmcnt(0)
	v_add_f32_e32 v18, v25, v17
	ds_bpermute_b32 v19, v115, v18
	v_ashrrev_i32_e32 v17, 31, v16
	v_lshlrev_b64 v[16:17], 11, v[16:17]
	v_lshl_add_u64 v[16:17], s[26:27], 0, v[16:17]
	v_lshl_add_u64 v[16:17], v[16:17], 0, s[30:31]
	s_waitcnt lgkmcnt(0)
	v_add_f32_e32 v18, v18, v19
	v_div_scale_f32 v19, s[62:63], v18, v18, 1.0
	v_rcp_f32_e32 v20, v19
	v_div_scale_f32 v21, vcc, 1.0, v18, 1.0
	v_lshl_add_u64 v[16:17], v[16:17], 0, v[98:99]
	v_fma_f32 v22, -v19, v20, 1.0
	v_fmac_f32_e32 v20, v22, v20
	v_mul_f32_e32 v22, v21, v20
	v_fma_f32 v23, -v19, v22, v21
	v_fmac_f32_e32 v22, v23, v20
	v_fma_f32 v19, -v19, v22, v21
	v_div_fmas_f32 v19, v19, v20, v22
	v_div_fixup_f32 v18, v19, v18, 1.0
	v_pk_mul_f32 v[12:13], v[12:13], v[18:19] op_sel_hi:[1,0]
	v_pk_mul_f32 v[14:15], v[14:15], v[18:19] op_sel_hi:[1,0]
	v_pk_mul_f32 v[8:9], v[8:9], v[18:19] op_sel_hi:[1,0]
	v_pk_mul_f32 v[10:11], v[10:11], v[18:19] op_sel_hi:[1,0]
	v_pk_mul_f32 v[4:5], v[4:5], v[18:19] op_sel_hi:[1,0]
	v_pk_mul_f32 v[6:7], v[6:7], v[18:19] op_sel_hi:[1,0]
	v_pk_mul_f32 v[0:1], v[0:1], v[18:19] op_sel_hi:[1,0]
	v_pk_mul_f32 v[2:3], v[2:3], v[18:19] op_sel_hi:[1,0]
	v_cvt_pk_bf16_f32 v12, v12, v13
	v_cvt_pk_bf16_f32 v13, v14, v15
	v_cvt_pk_bf16_f32 v8, v8, v9
	v_cvt_pk_bf16_f32 v9, v10, v11
	v_cvt_pk_bf16_f32 v4, v4, v5
	v_cvt_pk_bf16_f32 v5, v6, v7
	v_cvt_pk_bf16_f32 v0, v0, v1
	v_cvt_pk_bf16_f32 v1, v2, v3
	global_store_dwordx2 v[16:17], v[12:13], off offset:1024
	global_store_dwordx2 v[16:17], v[8:9], off offset:1056
	global_store_dwordx2 v[16:17], v[4:5], off offset:1088
	global_store_dwordx2 v[16:17], v[0:1], off offset:1120
	s_cbranch_scc1 .LBB0_306
